# P1: the 8 left-over units per XCD group go to the workgroups whose regular units have the cheapest epilogues (no rope units)
# speedup vs baseline: 1.1783x; 1.0092x over previous
.Lp01_next:
	s_cmp_lt_u32 s60, 8
	s_cbranch_scc1 .Lp01_reg
	s_cmp_gt_u32 s60, 8
	s_cbranch_scc1 .LBB0_181
	s_mov_b32 s66, 0x80700e01
	s_lshr_b32 s67, s66, s62
	s_bitcmp1_b32 s67, 0
	s_cbranch_scc0 .LBB0_181
.Lp01_reg:
	s_sub_i32 s96, s60, s63
	s_cmp_gt_u32 s96, 5
	s_cbranch_scc1 .Lp01_noprod
	s_mul_i32 s66, s96, 3
	s_add_i32 s66, s66, 6
	s_lshl_b32 s66, s66, 3
	s_add_i32 s66, s66, s61
	s_lshl_b32 s66, s66, 8
	s_lshl_b32 s67, s62, 3
	s_add_i32 s66, s66, s67
	s_add_i32 s66, s66, s74
	s_add_i32 s97, s66, 0x800
	s_add_i32 s98, s66, 0x1000
	v_mov_b32_e32 v86, 0x358637bd
	v_mov_b32_e32 v87, 0
	v_lshlrev_b32_e32 v88, 4, v190
	v_xor_b32_e32 v80, 1, v190
	v_lshlrev_b32_e32 v80, 2, v80
	v_xor_b32_e32 v81, 2, v190
	v_lshlrev_b32_e32 v81, 2, v81
	v_xor_b32_e32 v82, 4, v190
	v_lshlrev_b32_e32 v82, 2, v82
	v_xor_b32_e32 v83, 8, v190
	v_lshlrev_b32_e32 v83, 2, v83
	v_xor_b32_e32 v84, 16, v190
	v_lshlrev_b32_e32 v84, 2, v84
	v_xor_b32_e32 v85, 32, v190
	v_lshlrev_b32_e32 v85, 2, v85
	s_cmp_lt_u32 s66, 0x8000
	s_cselect_b32 s68, s12, s14
	s_cselect_b32 s69, s13, s15
	s_cselect_b32 s67, 0, 0x8000
	s_sub_u32 s67, s66, s67
	s_lshl_b32 s67, s67, 12
	s_add_u32 s68, s68, s67
	s_addc_u32 s69, s69, 0
	global_load_dwordx4 v[18:21], v88, s[68:69] offset:0 nt
	global_load_dwordx4 v[22:25], v88, s[68:69] offset:1024 nt
	global_load_dwordx4 v[26:29], v88, s[68:69] offset:2048 nt
	global_load_dwordx4 v[30:33], v88, s[68:69] offset:3072 nt
	s_cmp_lt_u32 s97, 0x8000
	s_cselect_b32 s70, s12, s14
	s_cselect_b32 s71, s13, s15
	s_cselect_b32 s67, 0, 0x8000
	s_sub_u32 s67, s97, s67
	s_lshl_b32 s67, s67, 12
	s_add_u32 s70, s70, s67
	s_addc_u32 s71, s71, 0
	global_load_dwordx4 v[34:37], v88, s[70:71] offset:0 nt
	global_load_dwordx4 v[38:41], v88, s[70:71] offset:1024 nt
	global_load_dwordx4 v[42:45], v88, s[70:71] offset:2048 nt
	global_load_dwordx4 v[46:49], v88, s[70:71] offset:3072 nt
	s_cmp_lt_u32 s98, 0x8000
	s_cselect_b32 s72, s12, s14
	s_cselect_b32 s73, s13, s15
	s_cselect_b32 s67, 0, 0x8000
	s_sub_u32 s67, s98, s67
	s_lshl_b32 s67, s67, 12
	s_add_u32 s72, s72, s67
	s_addc_u32 s73, s73, 0
	global_load_dwordx4 v[50:53], v88, s[72:73] offset:0 nt
	global_load_dwordx4 v[54:57], v88, s[72:73] offset:1024 nt
	global_load_dwordx4 v[58:61], v88, s[72:73] offset:2048 nt
	global_load_dwordx4 v[62:65], v88, s[72:73] offset:3072 nt
	s_lshl_b32 s67, s66, 11
	s_add_u32 s86, s42, s67
	s_addc_u32 s87, s43, 0
	s_waitcnt vmcnt(8)
	v_mul_f32_e32 v66, v19, v19
	v_mul_f32_e32 v67, v23, v23
	v_mul_f32_e32 v68, v27, v27
	v_fmac_f32_e32 v66, v18, v18
	v_fmac_f32_e32 v67, v22, v22
	v_mul_f32_e32 v69, v31, v31
	v_fmac_f32_e32 v68, v26, v26
	v_fmac_f32_e32 v66, v20, v20
	v_fmac_f32_e32 v67, v24, v24
	v_fmac_f32_e32 v69, v30, v30
	v_fmac_f32_e32 v68, v28, v28
	v_fmac_f32_e32 v66, v21, v21
	v_fmac_f32_e32 v67, v25, v25
	v_fmac_f32_e32 v69, v32, v32
	v_fmac_f32_e32 v68, v29, v29
	v_add_f32_e32 v66, v66, v67
	v_fmac_f32_e32 v69, v33, v33
	v_add_f32_e32 v66, v66, v68
	v_add_f32_e32 v72, v66, v69
	v_cvt_pk_bf16_f32 v18, v18, v19
	v_cvt_pk_bf16_f32 v19, v20, v21
	v_cvt_pk_bf16_f32 v20, v22, v23
	v_cvt_pk_bf16_f32 v21, v24, v25
	v_cvt_pk_bf16_f32 v22, v26, v27
	v_cvt_pk_bf16_f32 v23, v28, v29
	v_cvt_pk_bf16_f32 v24, v30, v31
	v_cvt_pk_bf16_f32 v25, v32, v33
	global_store_dwordx2 v188, v[18:19], s[86:87] offset:0
	global_store_dwordx2 v188, v[20:21], s[86:87] offset:512
	global_store_dwordx2 v188, v[22:23], s[86:87] offset:1024
	global_store_dwordx2 v188, v[24:25], s[86:87] offset:1536
	s_lshl_b32 s67, s97, 11
	s_add_u32 s88, s42, s67
	s_addc_u32 s89, s43, 0
	s_waitcnt vmcnt(8)
	v_mul_f32_e32 v66, v35, v35
	v_mul_f32_e32 v67, v39, v39
	v_mul_f32_e32 v68, v43, v43
	v_fmac_f32_e32 v66, v34, v34
	v_fmac_f32_e32 v67, v38, v38
	v_mul_f32_e32 v69, v47, v47
	v_fmac_f32_e32 v68, v42, v42
	v_fmac_f32_e32 v66, v36, v36
	v_fmac_f32_e32 v67, v40, v40
	v_fmac_f32_e32 v69, v46, v46
	v_fmac_f32_e32 v68, v44, v44
	v_fmac_f32_e32 v66, v37, v37
	v_fmac_f32_e32 v67, v41, v41
	v_fmac_f32_e32 v69, v48, v48
	v_fmac_f32_e32 v68, v45, v45
	v_add_f32_e32 v66, v66, v67
	v_fmac_f32_e32 v69, v49, v49
	v_add_f32_e32 v66, v66, v68
	v_add_f32_e32 v73, v66, v69
	v_cvt_pk_bf16_f32 v34, v34, v35
	v_cvt_pk_bf16_f32 v35, v36, v37
	v_cvt_pk_bf16_f32 v36, v38, v39
	v_cvt_pk_bf16_f32 v37, v40, v41
	v_cvt_pk_bf16_f32 v38, v42, v43
	v_cvt_pk_bf16_f32 v39, v44, v45
	v_cvt_pk_bf16_f32 v40, v46, v47
	v_cvt_pk_bf16_f32 v41, v48, v49
	global_store_dwordx2 v188, v[34:35], s[88:89] offset:0
	global_store_dwordx2 v188, v[36:37], s[88:89] offset:512
	global_store_dwordx2 v188, v[38:39], s[88:89] offset:1024
	global_store_dwordx2 v188, v[40:41], s[88:89] offset:1536
	s_lshl_b32 s67, s98, 11
	s_add_u32 s90, s42, s67
	s_addc_u32 s91, s43, 0
	s_waitcnt vmcnt(8)
	v_mul_f32_e32 v66, v51, v51
	v_mul_f32_e32 v67, v55, v55
	v_mul_f32_e32 v68, v59, v59
	v_fmac_f32_e32 v66, v50, v50
	v_fmac_f32_e32 v67, v54, v54
	v_mul_f32_e32 v69, v63, v63
	v_fmac_f32_e32 v68, v58, v58
	v_fmac_f32_e32 v66, v52, v52
	v_fmac_f32_e32 v67, v56, v56
	v_fmac_f32_e32 v69, v62, v62
	v_fmac_f32_e32 v68, v60, v60
	v_fmac_f32_e32 v66, v53, v53
	v_fmac_f32_e32 v67, v57, v57
	v_fmac_f32_e32 v69, v64, v64
	v_fmac_f32_e32 v68, v61, v61
	v_add_f32_e32 v66, v66, v67
	v_fmac_f32_e32 v69, v65, v65
	v_add_f32_e32 v66, v66, v68
	v_add_f32_e32 v74, v66, v69
	v_cvt_pk_bf16_f32 v50, v50, v51
	v_cvt_pk_bf16_f32 v51, v52, v53
	v_cvt_pk_bf16_f32 v52, v54, v55
	v_cvt_pk_bf16_f32 v53, v56, v57
	v_cvt_pk_bf16_f32 v54, v58, v59
	v_cvt_pk_bf16_f32 v55, v60, v61
	v_cvt_pk_bf16_f32 v56, v62, v63
	v_cvt_pk_bf16_f32 v57, v64, v65
	global_store_dwordx2 v188, v[50:51], s[90:91] offset:0
	global_store_dwordx2 v188, v[52:53], s[90:91] offset:512
	global_store_dwordx2 v188, v[54:55], s[90:91] offset:1024
	global_store_dwordx2 v188, v[56:57], s[90:91] offset:1536
	ds_bpermute_b32 v76, v80, v72
	ds_bpermute_b32 v77, v80, v73
	ds_bpermute_b32 v78, v80, v74
	s_waitcnt lgkmcnt(0)
	v_add_f32_e32 v72, v72, v76
	v_add_f32_e32 v73, v73, v77
	v_add_f32_e32 v74, v74, v78
	ds_bpermute_b32 v76, v81, v72
	ds_bpermute_b32 v77, v81, v73
	ds_bpermute_b32 v78, v81, v74
	s_waitcnt lgkmcnt(0)
	v_add_f32_e32 v72, v72, v76
	v_add_f32_e32 v73, v73, v77
	v_add_f32_e32 v74, v74, v78
	ds_bpermute_b32 v76, v82, v72
	ds_bpermute_b32 v77, v82, v73
	ds_bpermute_b32 v78, v82, v74
	s_waitcnt lgkmcnt(0)
	v_add_f32_e32 v72, v72, v76
	v_add_f32_e32 v73, v73, v77
	v_add_f32_e32 v74, v74, v78
	ds_bpermute_b32 v76, v83, v72
	ds_bpermute_b32 v77, v83, v73
	ds_bpermute_b32 v78, v83, v74
	s_waitcnt lgkmcnt(0)
	v_add_f32_e32 v72, v72, v76
	v_add_f32_e32 v73, v73, v77
	v_add_f32_e32 v74, v74, v78
	ds_bpermute_b32 v76, v84, v72
	ds_bpermute_b32 v77, v84, v73
	ds_bpermute_b32 v78, v84, v74
	s_waitcnt lgkmcnt(0)
	v_add_f32_e32 v72, v72, v76
	v_add_f32_e32 v73, v73, v77
	v_add_f32_e32 v74, v74, v78
	ds_bpermute_b32 v76, v85, v72
	ds_bpermute_b32 v77, v85, v73
	ds_bpermute_b32 v78, v85, v74
	s_waitcnt lgkmcnt(0)
	v_add_f32_e32 v72, v72, v76
	v_add_f32_e32 v73, v73, v77
	v_add_f32_e32 v74, v74, v78
	v_fmamk_f32 v72, v72, 0x3a800000, v86
	v_fmamk_f32 v73, v73, 0x3a800000, v86
	v_fmamk_f32 v74, v74, 0x3a800000, v86
	v_rsq_f32_e32 v72, v72
	v_rsq_f32_e32 v73, v73
	v_rsq_f32_e32 v74, v74
	s_nop 0
	s_mov_b64 s[94:95], exec
	s_mov_b64 exec, 1
	s_lshl_b32 s67, s66, 2
	s_add_u32 s92, s42, s67
	s_addc_u32 s93, s43, 0
	s_add_u32 s92, s92, 0x6000000
	s_addc_u32 s93, s93, 0
	global_store_dword v87, v72, s[92:93]
	s_lshl_b32 s67, s97, 2
	s_add_u32 s92, s42, s67
	s_addc_u32 s93, s43, 0
	s_add_u32 s92, s92, 0x6000000
	s_addc_u32 s93, s93, 0
	global_store_dword v87, v73, s[92:93]
	s_lshl_b32 s67, s98, 2
	s_add_u32 s92, s42, s67
	s_addc_u32 s93, s43, 0
	s_add_u32 s92, s92, 0x6000000
	s_addc_u32 s93, s93, 0
	global_store_dword v87, v74, s[92:93]
	s_mov_b64 exec, s[94:95]
	s_waitcnt vmcnt(0)
	s_barrier
	s_cmp_lg_u32 s74, 0
	s_cbranch_scc1 .Lp01_noprod
	s_lshl_b32 s66, s61, 3
	s_add_i32 s66, s66, s96
	s_lshl_b32 s66, s66, 2
	v_mov_b32_e32 v20, s66
	v_mov_b32_e32 v21, 1
	s_add_u32 s68, s42, 0x60d3c20
	s_addc_u32 s69, s43, 0
	s_mov_b64 s[94:95], exec
	s_mov_b64 exec, 1
	global_atomic_add v20, v21, s[68:69] sc1
	s_mov_b64 exec, s[94:95]

.Lp01_nowait:
	s_lshl_b32 s66, s60, 5
	s_add_i32 s66, s66, s62
	s_cmp_lt_u32 s60, 8
	s_cbranch_scc1 .Lp01_j
	s_lshl_b32 s66, 1, s62
	s_add_i32 s66, s66, -1
	s_and_b32 s66, s66, 0x80700e01
	s_bcnt1_i32_b32 s66, s66
	s_addk_i32 s66, 0x100
.Lp01_j:
	s_mul_i32 s67, s66, 0x2e9
	s_lshr_b32 s67, s67, 13
	s_mul_i32 s68, s67, 11
	s_sub_i32 s68, s66, s68
	s_lshl_b32 s67, s67, 3
	s_add_i32 s67, s67, s61
	s_mul_i32 s33, s67, 11
	s_add_i32 s33, s33, s68
	s_add_i32 s60, s60, 1
